# column-max side step with n = 2 folded in (12 instructions instead of 25, no v_readfirstlane) in the three side K-loops; side-job-free copy of the P1 bf16 loop
# speedup vs baseline: 1.0065x; 1.0026x over previous
.Lp1b_body:
	s_add_i32 s12, s75, 2
	s_add_u32 s30, s28, 0xfff00080
	s_addc_u32 s31, s29, -1
	s_cmp_eq_u32 s72, s75
	s_cselect_b32 s35, s68, s31
	s_cselect_b32 s34, s69, s30
	s_cselect_b32 s31, s70, s74
	s_cselect_b32 s30, s71, s73
	ds_read_b128 v[168:171], v160
	ds_read_b128 v[176:179], v160 offset:1024
	ds_read_b128 v[180:183], v160 offset:2048
	ds_read_b128 v[184:187], v160 offset:3072
	ds_read_b128 v[188:191], v160 offset:16384
	ds_read_b128 v[192:195], v160 offset:17408
	ds_read_b128 v[196:199], v160 offset:18432
	ds_read_b128 v[200:203], v160 offset:19456
	s_add_i32 m0, s49, 0xc000
	ds_read_b128 v[204:207], v163
	ds_read_b128 v[208:211], v163 offset:1024
	ds_read_b128 v[212:215], v163 offset:2048
	ds_read_b128 v[216:219], v163 offset:3072
	ds_read_b128 v[220:223], v163 offset:4096
	ds_read_b128 v[224:227], v163 offset:5120
	ds_read_b128 v[228:231], v163 offset:6144
	global_load_lds_dwordx4 v146, s[28:29]
	s_add_i32 m0, s49, 0xe000
	ds_read_b128 v[236:239], v163 offset:7168
	global_load_lds_dwordx4 v148, s[28:29]
	s_waitcnt vmcnt(8) lgkmcnt(0)
	s_barrier
	s_setprio 1
	v_mfma_f32_16x16x32_bf16 v[132:135], v[168:171], v[204:207], v[132:135]
	v_mfma_f32_16x16x32_bf16 v[128:131], v[180:183], v[204:207], v[128:131]
	v_mfma_f32_16x16x32_bf16 v[116:119], v[168:171], v[212:215], v[116:119]
	v_mfma_f32_16x16x32_bf16 v[112:115], v[180:183], v[212:215], v[112:115]
	v_mfma_f32_16x16x32_bf16 v[100:103], v[168:171], v[220:223], v[100:103]
	v_mfma_f32_16x16x32_bf16 v[96:99], v[180:183], v[220:223], v[96:99]
	v_mfma_f32_16x16x32_bf16 v[84:87], v[168:171], v[228:231], v[84:87]
	v_mfma_f32_16x16x32_bf16 v[80:83], v[180:183], v[228:231], v[80:83]
	v_mfma_f32_16x16x32_bf16 v[132:135], v[176:179], v[208:211], v[132:135]
	v_mfma_f32_16x16x32_bf16 v[128:131], v[184:187], v[208:211], v[128:131]
	v_mfma_f32_16x16x32_bf16 v[116:119], v[176:179], v[216:219], v[116:119]
	v_mfma_f32_16x16x32_bf16 v[112:115], v[184:187], v[216:219], v[112:115]
	v_mfma_f32_16x16x32_bf16 v[100:103], v[176:179], v[224:227], v[100:103]
	v_mfma_f32_16x16x32_bf16 v[96:99], v[184:187], v[224:227], v[96:99]
	v_mfma_f32_16x16x32_bf16 v[84:87], v[176:179], v[236:239], v[84:87]
	v_mfma_f32_16x16x32_bf16 v[80:83], v[184:187], v[236:239], v[80:83]
	s_setprio 0
	s_setprio 1
	v_mfma_f32_16x16x32_bf16 v[124:127], v[188:191], v[204:207], v[124:127]
	v_mfma_f32_16x16x32_bf16 v[120:123], v[196:199], v[204:207], v[120:123]
	v_mfma_f32_16x16x32_bf16 v[108:111], v[188:191], v[212:215], v[108:111]
	v_mfma_f32_16x16x32_bf16 v[104:107], v[196:199], v[212:215], v[104:107]
	v_mfma_f32_16x16x32_bf16 v[92:95], v[188:191], v[220:223], v[92:95]
	v_mfma_f32_16x16x32_bf16 v[88:91], v[196:199], v[220:223], v[88:91]
	v_mfma_f32_16x16x32_bf16 v[76:79], v[188:191], v[228:231], v[76:79]
	v_mfma_f32_16x16x32_bf16 v[72:75], v[196:199], v[228:231], v[72:75]
	v_mfma_f32_16x16x32_bf16 v[124:127], v[192:195], v[208:211], v[124:127]
	v_mfma_f32_16x16x32_bf16 v[120:123], v[200:203], v[208:211], v[120:123]
	v_mfma_f32_16x16x32_bf16 v[108:111], v[192:195], v[216:219], v[108:111]
	v_mfma_f32_16x16x32_bf16 v[104:107], v[200:203], v[216:219], v[104:107]
	v_mfma_f32_16x16x32_bf16 v[92:95], v[192:195], v[224:227], v[92:95]
	v_mfma_f32_16x16x32_bf16 v[88:91], v[200:203], v[224:227], v[88:91]
	v_mfma_f32_16x16x32_bf16 v[76:79], v[192:195], v[236:239], v[76:79]
	v_mfma_f32_16x16x32_bf16 v[72:75], v[200:203], v[236:239], v[72:75]
	s_setprio 0
	s_barrier
	s_add_i32 s36, s59, s48
	s_mov_b32 m0, s36
	ds_read_b128 v[204:207], v163 offset:16384
	ds_read_b128 v[208:211], v163 offset:17408
	ds_read_b128 v[212:215], v163 offset:18432
	ds_read_b128 v[216:219], v163 offset:19456
	global_load_lds_dwordx4 v138, s[30:31]
	s_add_i32 m0, s36, 0x2000
	s_add_u32 s36, s30, 0x100000
	s_addc_u32 s37, s31, 0
	s_add_i32 s75, s60, s48
	global_load_lds_dwordx4 v142, s[30:31]
	s_mov_b32 m0, s75
	ds_read_b128 v[236:239], v163 offset:23552
	global_load_lds_dwordx4 v138, s[36:37]
	s_add_i32 m0, s75, 0x2000
	ds_read_b128 v[228:231], v163 offset:22528
	global_load_lds_dwordx4 v142, s[36:37]
	s_mov_b32 m0, s49
	ds_read_b128 v[224:227], v163 offset:21504
	global_load_lds_dwordx4 v136, s[34:35]
	s_mov_b32 m0, s50
	ds_read_b128 v[220:223], v163 offset:20480
	global_load_lds_dwordx4 v140, s[34:35]
	s_waitcnt vmcnt(8) lgkmcnt(0)
	s_barrier
	s_setprio 1
	v_mfma_f32_16x16x32_bf16 v[68:71], v[168:171], v[204:207], v[68:71]
	v_mfma_f32_16x16x32_bf16 v[64:67], v[180:183], v[204:207], v[64:67]
	v_mfma_f32_16x16x32_bf16 v[52:55], v[168:171], v[212:215], v[52:55]
	v_mfma_f32_16x16x32_bf16 v[48:51], v[180:183], v[212:215], v[48:51]
	v_mfma_f32_16x16x32_bf16 v[36:39], v[168:171], v[220:223], v[36:39]
	v_mfma_f32_16x16x32_bf16 v[32:35], v[180:183], v[220:223], v[32:35]
	v_mfma_f32_16x16x32_bf16 v[20:23], v[168:171], v[228:231], v[20:23]
	v_mfma_f32_16x16x32_bf16 v[16:19], v[180:183], v[228:231], v[16:19]
	v_mfma_f32_16x16x32_bf16 v[68:71], v[176:179], v[208:211], v[68:71]
	v_mfma_f32_16x16x32_bf16 v[64:67], v[184:187], v[208:211], v[64:67]
	v_mfma_f32_16x16x32_bf16 v[52:55], v[176:179], v[216:219], v[52:55]
	v_mfma_f32_16x16x32_bf16 v[48:51], v[184:187], v[216:219], v[48:51]
	v_mfma_f32_16x16x32_bf16 v[36:39], v[176:179], v[224:227], v[36:39]
	v_mfma_f32_16x16x32_bf16 v[32:35], v[184:187], v[224:227], v[32:35]
	v_mfma_f32_16x16x32_bf16 v[20:23], v[176:179], v[236:239], v[20:23]
	v_mfma_f32_16x16x32_bf16 v[16:19], v[184:187], v[236:239], v[16:19]
	s_setprio 0
	s_setprio 1
	v_mfma_f32_16x16x32_bf16 v[60:63], v[188:191], v[204:207], v[60:63]
	v_mfma_f32_16x16x32_bf16 v[56:59], v[196:199], v[204:207], v[56:59]
	v_mfma_f32_16x16x32_bf16 v[44:47], v[188:191], v[212:215], v[44:47]
	v_mfma_f32_16x16x32_bf16 v[40:43], v[196:199], v[212:215], v[40:43]
	v_mfma_f32_16x16x32_bf16 v[28:31], v[188:191], v[220:223], v[28:31]
	v_mfma_f32_16x16x32_bf16 v[24:27], v[196:199], v[220:223], v[24:27]
	v_mfma_f32_16x16x32_bf16 v[12:15], v[188:191], v[228:231], v[12:15]
	v_mfma_f32_16x16x32_bf16 v[6:9], v[196:199], v[228:231], v[8:11]
	v_mfma_f32_16x16x32_bf16 v[60:63], v[192:195], v[208:211], v[60:63]
	v_mfma_f32_16x16x32_bf16 v[56:59], v[200:203], v[208:211], v[56:59]
	v_mfma_f32_16x16x32_bf16 v[44:47], v[192:195], v[216:219], v[44:47]
	v_mfma_f32_16x16x32_bf16 v[40:43], v[200:203], v[216:219], v[40:43]
	v_mfma_f32_16x16x32_bf16 v[28:31], v[192:195], v[224:227], v[28:31]
	v_mfma_f32_16x16x32_bf16 v[24:27], v[200:203], v[224:227], v[24:27]
	v_mfma_f32_16x16x32_bf16 v[12:15], v[192:195], v[236:239], v[12:15]
	v_mfma_f32_16x16x32_bf16 v[6:9], v[200:203], v[236:239], v[6:9]
	s_setprio 0
	s_barrier
	s_add_i32 s36, 0, 0x18000
	s_add_i32 s37, 0, 0x1c000
	ds_read_b128 v[168:171], v160 offset:32768
	ds_read_b128 v[176:179], v160 offset:33792
	ds_read_b128 v[180:183], v160 offset:34816
	ds_read_b128 v[184:187], v160 offset:35840
	ds_read_b128 v[188:191], v160 offset:49152
	ds_read_b128 v[192:195], v160 offset:50176
	ds_read_b128 v[196:199], v160 offset:51200
	ds_read_b128 v[200:203], v160 offset:52224
	s_add_u32 s34, s34, 0x100000
	s_addc_u32 s35, s35, 0
	s_mov_b32 m0, s51
	ds_read_b128 v[204:207], v163 offset:32768
	ds_read_b128 v[208:211], v163 offset:33792
	ds_read_b128 v[212:215], v163 offset:34816
	ds_read_b128 v[216:219], v163 offset:35840
	ds_read_b128 v[220:223], v163 offset:36864
	ds_read_b128 v[224:227], v163 offset:37888
	ds_read_b128 v[228:231], v163 offset:38912
	global_load_lds_dwordx4 v136, s[34:35]
	s_mov_b32 m0, s52
	ds_read_b128 v[236:239], v163 offset:39936
	global_load_lds_dwordx4 v140, s[34:35]
	s_waitcnt vmcnt(8) lgkmcnt(0)
	s_barrier
	s_setprio 1
	v_mfma_f32_16x16x32_bf16 v[132:135], v[168:171], v[204:207], v[132:135]
	v_mfma_f32_16x16x32_bf16 v[128:131], v[180:183], v[204:207], v[128:131]
	v_mfma_f32_16x16x32_bf16 v[116:119], v[168:171], v[212:215], v[116:119]
	v_mfma_f32_16x16x32_bf16 v[112:115], v[180:183], v[212:215], v[112:115]
	v_mfma_f32_16x16x32_bf16 v[100:103], v[168:171], v[220:223], v[100:103]
	v_mfma_f32_16x16x32_bf16 v[96:99], v[180:183], v[220:223], v[96:99]
	v_mfma_f32_16x16x32_bf16 v[84:87], v[168:171], v[228:231], v[84:87]
	v_mfma_f32_16x16x32_bf16 v[80:83], v[180:183], v[228:231], v[80:83]
	v_mfma_f32_16x16x32_bf16 v[132:135], v[176:179], v[208:211], v[132:135]
	v_mfma_f32_16x16x32_bf16 v[128:131], v[184:187], v[208:211], v[128:131]
	v_mfma_f32_16x16x32_bf16 v[116:119], v[176:179], v[216:219], v[116:119]
	v_mfma_f32_16x16x32_bf16 v[112:115], v[184:187], v[216:219], v[112:115]
	v_mfma_f32_16x16x32_bf16 v[100:103], v[176:179], v[224:227], v[100:103]
	v_mfma_f32_16x16x32_bf16 v[96:99], v[184:187], v[224:227], v[96:99]
	v_mfma_f32_16x16x32_bf16 v[84:87], v[176:179], v[236:239], v[84:87]
	v_mfma_f32_16x16x32_bf16 v[80:83], v[184:187], v[236:239], v[80:83]
	s_setprio 0
	s_setprio 1
	v_mfma_f32_16x16x32_bf16 v[124:127], v[188:191], v[204:207], v[124:127]
	v_mfma_f32_16x16x32_bf16 v[120:123], v[196:199], v[204:207], v[120:123]
	v_mfma_f32_16x16x32_bf16 v[108:111], v[188:191], v[212:215], v[108:111]
	v_mfma_f32_16x16x32_bf16 v[104:107], v[196:199], v[212:215], v[104:107]
	v_mfma_f32_16x16x32_bf16 v[92:95], v[188:191], v[220:223], v[92:95]
	v_mfma_f32_16x16x32_bf16 v[88:91], v[196:199], v[220:223], v[88:91]
	v_mfma_f32_16x16x32_bf16 v[76:79], v[188:191], v[228:231], v[76:79]
	v_mfma_f32_16x16x32_bf16 v[72:75], v[196:199], v[228:231], v[72:75]
	v_mfma_f32_16x16x32_bf16 v[124:127], v[192:195], v[208:211], v[124:127]
	v_mfma_f32_16x16x32_bf16 v[120:123], v[200:203], v[208:211], v[120:123]
	v_mfma_f32_16x16x32_bf16 v[108:111], v[192:195], v[216:219], v[108:111]
	v_mfma_f32_16x16x32_bf16 v[104:107], v[200:203], v[216:219], v[104:107]
	v_mfma_f32_16x16x32_bf16 v[92:95], v[192:195], v[224:227], v[92:95]
	v_mfma_f32_16x16x32_bf16 v[88:91], v[200:203], v[224:227], v[88:91]
	v_mfma_f32_16x16x32_bf16 v[76:79], v[192:195], v[236:239], v[76:79]
	v_mfma_f32_16x16x32_bf16 v[72:75], v[200:203], v[236:239], v[72:75]
	s_setprio 0
	s_barrier
	s_add_u32 s98, s30, s10
	s_addc_u32 s99, s31, s11
	s_add_u32 s100, s34, s10
	s_addc_u32 s101, s35, s11
	s_sub_u32 s100, s100, 0x100000
	s_subb_u32 s101, s101, 0
	s_add_i32 s34, s36, s48
	s_mov_b32 m0, s34
	ds_read_b128 v[152:155], v163 offset:49152
	ds_read_b128 v[164:167], v163 offset:50176
	ds_read_b128 v[204:207], v163 offset:51200
	ds_read_b128 v[208:211], v163 offset:52224
	global_load_lds_dwordx4 v138, s[98:99]
	s_add_i32 m0, s34, 0x2000
	s_add_u32 s30, s30, 0x100080
	s_addc_u32 s31, s31, 0
	s_add_i32 s34, s37, s48
	global_load_lds_dwordx4 v142, s[98:99]
	s_mov_b32 m0, s34
	ds_read_b128 v[224:227], v163 offset:56320
	global_load_lds_dwordx4 v138, s[30:31]
	s_add_i32 m0, s34, 0x2000
	ds_read_b128 v[220:223], v163 offset:55296
	global_load_lds_dwordx4 v142, s[30:31]
	s_mov_b32 m0, s56
	ds_read_b128 v[216:219], v163 offset:54272
	global_load_lds_dwordx4 v136, s[100:101]
	s_mov_b32 m0, s57
	ds_read_b128 v[212:215], v163 offset:53248
	global_load_lds_dwordx4 v140, s[100:101]
	s_waitcnt vmcnt(8) lgkmcnt(0)
	s_barrier
	s_setprio 1
	v_mfma_f32_16x16x32_bf16 v[68:71], v[168:171], v[152:155], v[68:71]
	v_mfma_f32_16x16x32_bf16 v[64:67], v[180:183], v[152:155], v[64:67]
	v_mfma_f32_16x16x32_bf16 v[52:55], v[168:171], v[204:207], v[52:55]
	v_mfma_f32_16x16x32_bf16 v[48:51], v[180:183], v[204:207], v[48:51]
	v_mfma_f32_16x16x32_bf16 v[36:39], v[168:171], v[212:215], v[36:39]
	v_mfma_f32_16x16x32_bf16 v[32:35], v[180:183], v[212:215], v[32:35]
	v_mfma_f32_16x16x32_bf16 v[20:23], v[168:171], v[220:223], v[20:23]
	v_mfma_f32_16x16x32_bf16 v[16:19], v[180:183], v[220:223], v[16:19]
	v_mfma_f32_16x16x32_bf16 v[68:71], v[176:179], v[164:167], v[68:71]
	v_mfma_f32_16x16x32_bf16 v[64:67], v[184:187], v[164:167], v[64:67]
	v_mfma_f32_16x16x32_bf16 v[52:55], v[176:179], v[208:211], v[52:55]
	v_mfma_f32_16x16x32_bf16 v[48:51], v[184:187], v[208:211], v[48:51]
	v_mfma_f32_16x16x32_bf16 v[36:39], v[176:179], v[216:219], v[36:39]
	v_mfma_f32_16x16x32_bf16 v[32:35], v[184:187], v[216:219], v[32:35]
	v_mfma_f32_16x16x32_bf16 v[20:23], v[176:179], v[224:227], v[20:23]
	v_mfma_f32_16x16x32_bf16 v[16:19], v[184:187], v[224:227], v[16:19]
	s_setprio 0
	s_setprio 1
	v_mfma_f32_16x16x32_bf16 v[60:63], v[188:191], v[152:155], v[60:63]
	v_mfma_f32_16x16x32_bf16 v[56:59], v[196:199], v[152:155], v[56:59]
	v_mfma_f32_16x16x32_bf16 v[44:47], v[188:191], v[204:207], v[44:47]
	v_mfma_f32_16x16x32_bf16 v[40:43], v[196:199], v[204:207], v[40:43]
	v_mfma_f32_16x16x32_bf16 v[28:31], v[188:191], v[212:215], v[28:31]
	v_mfma_f32_16x16x32_bf16 v[24:27], v[196:199], v[212:215], v[24:27]
	v_mfma_f32_16x16x32_bf16 v[10:13], v[188:191], v[220:223], v[12:15]
	v_mfma_f32_16x16x32_bf16 v[6:9], v[196:199], v[220:223], v[6:9]
	v_mfma_f32_16x16x32_bf16 v[60:63], v[192:195], v[164:167], v[60:63]
	v_mfma_f32_16x16x32_bf16 v[56:59], v[200:203], v[164:167], v[56:59]
	v_mfma_f32_16x16x32_bf16 v[44:47], v[192:195], v[208:211], v[44:47]
	v_mfma_f32_16x16x32_bf16 v[40:43], v[200:203], v[208:211], v[40:43]
	v_mfma_f32_16x16x32_bf16 v[28:31], v[192:195], v[216:219], v[28:31]
	v_mfma_f32_16x16x32_bf16 v[24:27], v[200:203], v[216:219], v[24:27]
	v_mfma_f32_16x16x32_bf16 v[12:15], v[192:195], v[224:227], v[10:13]
	v_mfma_f32_16x16x32_bf16 v[8:11], v[200:203], v[224:227], v[6:9]
	s_setprio 0
	s_barrier
	s_add_u32 s28, s28, 0x100
	s_addc_u32 s29, s29, 0
	s_add_u32 s73, s73, 0x100
	s_addc_u32 s74, s74, 0
	s_cmp_ge_i32 s12, s67
	s_cbranch_scc0 .Lp1b_top
	s_branch .Lp1b_epi

.LBB0_236:
	s_add_i32 s12, s75, 2
	s_add_u32 s30, s28, 0xfff00080
	s_addc_u32 s31, s29, -1
	s_cmp_eq_u32 s72, s75
	s_cselect_b32 s35, s68, s31
	s_cselect_b32 s34, s69, s30
	s_cselect_b32 s31, s70, s74
	s_cselect_b32 s30, s71, s73
	s_cmpk_lt_i32 s3, 0x56
	s_mov_b32 s78, 0xac00
	s_cselect_b32 s75, s78, 0x4000
	s_mul_i32 s36, s75, s33
	s_add_u32 s36, s38, s36
	s_addc_u32 s37, s39, 0
	global_load_dwordx4 v[152:155], v173, s[36:37] nt
	s_add_u32 s76, s36, s75
	s_addc_u32 s77, s37, 0
	global_load_dwordx4 v[164:167], v173, s[76:77] nt
	s_add_i32 s33, s33, 2
	v_add_u32_e32 v174, -2, v174
	ds_read_b128 v[168:171], v160
	ds_read_b128 v[176:179], v160 offset:1024
	ds_read_b128 v[180:183], v160 offset:2048
	ds_read_b128 v[184:187], v160 offset:3072
	ds_read_b128 v[188:191], v160 offset:16384
	ds_read_b128 v[192:195], v160 offset:17408
	ds_read_b128 v[196:199], v160 offset:18432
	ds_read_b128 v[200:203], v160 offset:19456
	s_add_i32 m0, s49, 0xc000
	ds_read_b128 v[204:207], v163
	ds_read_b128 v[208:211], v163 offset:1024
	ds_read_b128 v[212:215], v163 offset:2048
	ds_read_b128 v[216:219], v163 offset:3072
	ds_read_b128 v[220:223], v163 offset:4096
	ds_read_b128 v[224:227], v163 offset:5120
	ds_read_b128 v[228:231], v163 offset:6144
	global_load_lds_dwordx4 v146, s[28:29]
	s_add_i32 m0, s49, 0xe000
	ds_read_b128 v[236:239], v163 offset:7168
	global_load_lds_dwordx4 v148, s[28:29]
	s_waitcnt vmcnt(10) lgkmcnt(0)
	s_barrier
	s_setprio 1
	v_mfma_f32_16x16x32_bf16 v[132:135], v[168:171], v[204:207], v[132:135]
	v_mfma_f32_16x16x32_bf16 v[128:131], v[180:183], v[204:207], v[128:131]
	v_mfma_f32_16x16x32_bf16 v[116:119], v[168:171], v[212:215], v[116:119]
	v_mfma_f32_16x16x32_bf16 v[112:115], v[180:183], v[212:215], v[112:115]
	v_mfma_f32_16x16x32_bf16 v[100:103], v[168:171], v[220:223], v[100:103]
	v_mfma_f32_16x16x32_bf16 v[96:99], v[180:183], v[220:223], v[96:99]
	v_mfma_f32_16x16x32_bf16 v[84:87], v[168:171], v[228:231], v[84:87]
	v_mfma_f32_16x16x32_bf16 v[80:83], v[180:183], v[228:231], v[80:83]
	v_mfma_f32_16x16x32_bf16 v[132:135], v[176:179], v[208:211], v[132:135]
	v_mfma_f32_16x16x32_bf16 v[128:131], v[184:187], v[208:211], v[128:131]
	v_mfma_f32_16x16x32_bf16 v[116:119], v[176:179], v[216:219], v[116:119]
	v_mfma_f32_16x16x32_bf16 v[112:115], v[184:187], v[216:219], v[112:115]
	v_mfma_f32_16x16x32_bf16 v[100:103], v[176:179], v[224:227], v[100:103]
	v_mfma_f32_16x16x32_bf16 v[96:99], v[184:187], v[224:227], v[96:99]
	v_mfma_f32_16x16x32_bf16 v[84:87], v[176:179], v[236:239], v[84:87]
	v_mfma_f32_16x16x32_bf16 v[80:83], v[184:187], v[236:239], v[80:83]
	s_setprio 0
	s_setprio 1
	v_mfma_f32_16x16x32_bf16 v[124:127], v[188:191], v[204:207], v[124:127]
	v_mfma_f32_16x16x32_bf16 v[120:123], v[196:199], v[204:207], v[120:123]
	v_mfma_f32_16x16x32_bf16 v[108:111], v[188:191], v[212:215], v[108:111]
	v_mfma_f32_16x16x32_bf16 v[104:107], v[196:199], v[212:215], v[104:107]
	v_mfma_f32_16x16x32_bf16 v[92:95], v[188:191], v[220:223], v[92:95]
	v_mfma_f32_16x16x32_bf16 v[88:91], v[196:199], v[220:223], v[88:91]
	v_mfma_f32_16x16x32_bf16 v[76:79], v[188:191], v[228:231], v[76:79]
	v_mfma_f32_16x16x32_bf16 v[72:75], v[196:199], v[228:231], v[72:75]
	v_mfma_f32_16x16x32_bf16 v[124:127], v[192:195], v[208:211], v[124:127]
	v_mfma_f32_16x16x32_bf16 v[120:123], v[200:203], v[208:211], v[120:123]
	v_mfma_f32_16x16x32_bf16 v[108:111], v[192:195], v[216:219], v[108:111]
	v_mfma_f32_16x16x32_bf16 v[104:107], v[200:203], v[216:219], v[104:107]
	v_mfma_f32_16x16x32_bf16 v[92:95], v[192:195], v[224:227], v[92:95]
	v_mfma_f32_16x16x32_bf16 v[88:91], v[200:203], v[224:227], v[88:91]
	v_mfma_f32_16x16x32_bf16 v[76:79], v[192:195], v[236:239], v[76:79]
	v_mfma_f32_16x16x32_bf16 v[72:75], v[200:203], v[236:239], v[72:75]
	s_setprio 0
	s_barrier
	s_add_i32 s36, s59, s48
	s_mov_b32 m0, s36
	ds_read_b128 v[204:207], v163 offset:16384
	ds_read_b128 v[208:211], v163 offset:17408
	ds_read_b128 v[212:215], v163 offset:18432
	ds_read_b128 v[216:219], v163 offset:19456
	global_load_lds_dwordx4 v138, s[30:31]
	s_add_i32 m0, s36, 0x2000
	s_add_u32 s36, s30, 0x100000
	s_addc_u32 s37, s31, 0
	s_add_i32 s75, s60, s48
	global_load_lds_dwordx4 v142, s[30:31]
	s_mov_b32 m0, s75
	ds_read_b128 v[236:239], v163 offset:23552
	global_load_lds_dwordx4 v138, s[36:37]
	s_add_i32 m0, s75, 0x2000
	ds_read_b128 v[228:231], v163 offset:22528
	global_load_lds_dwordx4 v142, s[36:37]
	s_mov_b32 m0, s49
	ds_read_b128 v[224:227], v163 offset:21504
	global_load_lds_dwordx4 v136, s[34:35]
	s_mov_b32 m0, s50
	ds_read_b128 v[220:223], v163 offset:20480
	global_load_lds_dwordx4 v140, s[34:35]
	s_waitcnt vmcnt(10) lgkmcnt(0)
	s_barrier
	s_setprio 1
	v_mfma_f32_16x16x32_bf16 v[68:71], v[168:171], v[204:207], v[68:71]
	v_mfma_f32_16x16x32_bf16 v[64:67], v[180:183], v[204:207], v[64:67]
	v_mfma_f32_16x16x32_bf16 v[52:55], v[168:171], v[212:215], v[52:55]
	v_mfma_f32_16x16x32_bf16 v[48:51], v[180:183], v[212:215], v[48:51]
	v_mfma_f32_16x16x32_bf16 v[36:39], v[168:171], v[220:223], v[36:39]
	v_mfma_f32_16x16x32_bf16 v[32:35], v[180:183], v[220:223], v[32:35]
	v_mfma_f32_16x16x32_bf16 v[20:23], v[168:171], v[228:231], v[20:23]
	v_mfma_f32_16x16x32_bf16 v[16:19], v[180:183], v[228:231], v[16:19]
	v_mfma_f32_16x16x32_bf16 v[68:71], v[176:179], v[208:211], v[68:71]
	v_mfma_f32_16x16x32_bf16 v[64:67], v[184:187], v[208:211], v[64:67]
	v_mfma_f32_16x16x32_bf16 v[52:55], v[176:179], v[216:219], v[52:55]
	v_mfma_f32_16x16x32_bf16 v[48:51], v[184:187], v[216:219], v[48:51]
	v_mfma_f32_16x16x32_bf16 v[36:39], v[176:179], v[224:227], v[36:39]
	v_mfma_f32_16x16x32_bf16 v[32:35], v[184:187], v[224:227], v[32:35]
	v_mfma_f32_16x16x32_bf16 v[20:23], v[176:179], v[236:239], v[20:23]
	v_mfma_f32_16x16x32_bf16 v[16:19], v[184:187], v[236:239], v[16:19]
	s_setprio 0
	s_setprio 1
	v_mfma_f32_16x16x32_bf16 v[60:63], v[188:191], v[204:207], v[60:63]
	v_mfma_f32_16x16x32_bf16 v[56:59], v[196:199], v[204:207], v[56:59]
	v_mfma_f32_16x16x32_bf16 v[44:47], v[188:191], v[212:215], v[44:47]
	v_mfma_f32_16x16x32_bf16 v[40:43], v[196:199], v[212:215], v[40:43]
	v_mfma_f32_16x16x32_bf16 v[28:31], v[188:191], v[220:223], v[28:31]
	v_mfma_f32_16x16x32_bf16 v[24:27], v[196:199], v[220:223], v[24:27]
	v_mfma_f32_16x16x32_bf16 v[12:15], v[188:191], v[228:231], v[12:15]
	v_mfma_f32_16x16x32_bf16 v[6:9], v[196:199], v[228:231], v[8:11]
	v_mfma_f32_16x16x32_bf16 v[60:63], v[192:195], v[208:211], v[60:63]
	v_mfma_f32_16x16x32_bf16 v[56:59], v[200:203], v[208:211], v[56:59]
	v_mfma_f32_16x16x32_bf16 v[44:47], v[192:195], v[216:219], v[44:47]
	v_mfma_f32_16x16x32_bf16 v[40:43], v[200:203], v[216:219], v[40:43]
	v_mfma_f32_16x16x32_bf16 v[28:31], v[192:195], v[224:227], v[28:31]
	v_mfma_f32_16x16x32_bf16 v[24:27], v[200:203], v[224:227], v[24:27]
	v_mfma_f32_16x16x32_bf16 v[12:15], v[192:195], v[236:239], v[12:15]
	v_mfma_f32_16x16x32_bf16 v[6:9], v[200:203], v[236:239], v[6:9]
	s_setprio 0
	s_barrier
	s_add_i32 s36, 0, 0x18000
	s_add_i32 s37, 0, 0x1c000
	ds_read_b128 v[168:171], v160 offset:32768
	ds_read_b128 v[176:179], v160 offset:33792
	ds_read_b128 v[180:183], v160 offset:34816
	ds_read_b128 v[184:187], v160 offset:35840
	ds_read_b128 v[188:191], v160 offset:49152
	ds_read_b128 v[192:195], v160 offset:50176
	ds_read_b128 v[196:199], v160 offset:51200
	ds_read_b128 v[200:203], v160 offset:52224
	s_add_u32 s34, s34, 0x100000
	s_addc_u32 s35, s35, 0
	s_mov_b32 m0, s51
	ds_read_b128 v[204:207], v163 offset:32768
	ds_read_b128 v[208:211], v163 offset:33792
	ds_read_b128 v[212:215], v163 offset:34816
	ds_read_b128 v[216:219], v163 offset:35840
	ds_read_b128 v[220:223], v163 offset:36864
	ds_read_b128 v[224:227], v163 offset:37888
	ds_read_b128 v[228:231], v163 offset:38912
	global_load_lds_dwordx4 v136, s[34:35]
	s_mov_b32 m0, s52
	ds_read_b128 v[236:239], v163 offset:39936
	global_load_lds_dwordx4 v140, s[34:35]
	s_waitcnt vmcnt(8) lgkmcnt(0)
	s_barrier
	s_setprio 1
	v_mfma_f32_16x16x32_bf16 v[132:135], v[168:171], v[204:207], v[132:135]
	v_mfma_f32_16x16x32_bf16 v[128:131], v[180:183], v[204:207], v[128:131]
	v_mfma_f32_16x16x32_bf16 v[116:119], v[168:171], v[212:215], v[116:119]
	v_mfma_f32_16x16x32_bf16 v[112:115], v[180:183], v[212:215], v[112:115]
	v_mfma_f32_16x16x32_bf16 v[100:103], v[168:171], v[220:223], v[100:103]
	v_max3_f32 v0, v0, |v152|, |v164|
	v_mfma_f32_16x16x32_bf16 v[96:99], v[180:183], v[220:223], v[96:99]
	v_max3_f32 v1, v1, |v153|, |v165|
	v_mfma_f32_16x16x32_bf16 v[84:87], v[168:171], v[228:231], v[84:87]
	v_max3_f32 v2, v2, |v154|, |v166|
	v_mfma_f32_16x16x32_bf16 v[80:83], v[180:183], v[228:231], v[80:83]
	v_max3_f32 v3, v3, |v155|, |v167|
	v_mfma_f32_16x16x32_bf16 v[132:135], v[176:179], v[208:211], v[132:135]
	v_mfma_f32_16x16x32_bf16 v[128:131], v[184:187], v[208:211], v[128:131]
	v_mfma_f32_16x16x32_bf16 v[116:119], v[176:179], v[216:219], v[116:119]
	v_mfma_f32_16x16x32_bf16 v[112:115], v[184:187], v[216:219], v[112:115]
	v_mfma_f32_16x16x32_bf16 v[100:103], v[176:179], v[224:227], v[100:103]
	v_mfma_f32_16x16x32_bf16 v[96:99], v[184:187], v[224:227], v[96:99]
	v_mfma_f32_16x16x32_bf16 v[84:87], v[176:179], v[236:239], v[84:87]
	v_mfma_f32_16x16x32_bf16 v[80:83], v[184:187], v[236:239], v[80:83]
	s_setprio 0
	s_setprio 1
	v_mfma_f32_16x16x32_bf16 v[124:127], v[188:191], v[204:207], v[124:127]
	v_mfma_f32_16x16x32_bf16 v[120:123], v[196:199], v[204:207], v[120:123]
	v_mfma_f32_16x16x32_bf16 v[108:111], v[188:191], v[212:215], v[108:111]
	v_mfma_f32_16x16x32_bf16 v[104:107], v[196:199], v[212:215], v[104:107]
	v_mfma_f32_16x16x32_bf16 v[92:95], v[188:191], v[220:223], v[92:95]
	v_mfma_f32_16x16x32_bf16 v[88:91], v[196:199], v[220:223], v[88:91]
	v_mfma_f32_16x16x32_bf16 v[76:79], v[188:191], v[228:231], v[76:79]
	v_mfma_f32_16x16x32_bf16 v[72:75], v[196:199], v[228:231], v[72:75]
	v_mfma_f32_16x16x32_bf16 v[124:127], v[192:195], v[208:211], v[124:127]
	v_mfma_f32_16x16x32_bf16 v[120:123], v[200:203], v[208:211], v[120:123]
	v_mfma_f32_16x16x32_bf16 v[108:111], v[192:195], v[216:219], v[108:111]
	v_mfma_f32_16x16x32_bf16 v[104:107], v[200:203], v[216:219], v[104:107]
	v_mfma_f32_16x16x32_bf16 v[92:95], v[192:195], v[224:227], v[92:95]
	v_mfma_f32_16x16x32_bf16 v[88:91], v[200:203], v[224:227], v[88:91]
	v_mfma_f32_16x16x32_bf16 v[76:79], v[192:195], v[236:239], v[76:79]
	v_mfma_f32_16x16x32_bf16 v[72:75], v[200:203], v[236:239], v[72:75]
	s_setprio 0
	s_barrier
	s_add_u32 s98, s30, s10
	s_addc_u32 s99, s31, s11
	s_add_u32 s100, s34, s10
	s_addc_u32 s101, s35, s11
	s_sub_u32 s100, s100, 0x100000
	s_subb_u32 s101, s101, 0
	s_add_i32 s34, s36, s48
	s_mov_b32 m0, s34
	ds_read_b128 v[152:155], v163 offset:49152
	ds_read_b128 v[164:167], v163 offset:50176
	ds_read_b128 v[204:207], v163 offset:51200
	ds_read_b128 v[208:211], v163 offset:52224
	global_load_lds_dwordx4 v138, s[98:99]
	s_add_i32 m0, s34, 0x2000
	s_add_u32 s30, s30, 0x100080
	s_addc_u32 s31, s31, 0
	s_add_i32 s34, s37, s48
	global_load_lds_dwordx4 v142, s[98:99]
	s_mov_b32 m0, s34
	ds_read_b128 v[224:227], v163 offset:56320
	global_load_lds_dwordx4 v138, s[30:31]
	s_add_i32 m0, s34, 0x2000
	ds_read_b128 v[220:223], v163 offset:55296
	global_load_lds_dwordx4 v142, s[30:31]
	s_mov_b32 m0, s56
	ds_read_b128 v[216:219], v163 offset:54272
	global_load_lds_dwordx4 v136, s[100:101]
	s_mov_b32 m0, s57
	ds_read_b128 v[212:215], v163 offset:53248
	global_load_lds_dwordx4 v140, s[100:101]
	s_waitcnt vmcnt(8) lgkmcnt(0)
	s_barrier
	s_setprio 1
	v_mfma_f32_16x16x32_bf16 v[68:71], v[168:171], v[152:155], v[68:71]
	v_mfma_f32_16x16x32_bf16 v[64:67], v[180:183], v[152:155], v[64:67]
	v_mfma_f32_16x16x32_bf16 v[52:55], v[168:171], v[204:207], v[52:55]
	v_mfma_f32_16x16x32_bf16 v[48:51], v[180:183], v[204:207], v[48:51]
	v_mfma_f32_16x16x32_bf16 v[36:39], v[168:171], v[212:215], v[36:39]
	v_mfma_f32_16x16x32_bf16 v[32:35], v[180:183], v[212:215], v[32:35]
	v_mfma_f32_16x16x32_bf16 v[20:23], v[168:171], v[220:223], v[20:23]
	v_mfma_f32_16x16x32_bf16 v[16:19], v[180:183], v[220:223], v[16:19]
	v_mfma_f32_16x16x32_bf16 v[68:71], v[176:179], v[164:167], v[68:71]
	v_mfma_f32_16x16x32_bf16 v[64:67], v[184:187], v[164:167], v[64:67]
	v_mfma_f32_16x16x32_bf16 v[52:55], v[176:179], v[208:211], v[52:55]
	v_mfma_f32_16x16x32_bf16 v[48:51], v[184:187], v[208:211], v[48:51]
	v_mfma_f32_16x16x32_bf16 v[36:39], v[176:179], v[216:219], v[36:39]
	v_mfma_f32_16x16x32_bf16 v[32:35], v[184:187], v[216:219], v[32:35]
	v_mfma_f32_16x16x32_bf16 v[20:23], v[176:179], v[224:227], v[20:23]
	v_mfma_f32_16x16x32_bf16 v[16:19], v[184:187], v[224:227], v[16:19]
	s_setprio 0
	s_setprio 1
	v_mfma_f32_16x16x32_bf16 v[60:63], v[188:191], v[152:155], v[60:63]
	v_mfma_f32_16x16x32_bf16 v[56:59], v[196:199], v[152:155], v[56:59]
	v_mfma_f32_16x16x32_bf16 v[44:47], v[188:191], v[204:207], v[44:47]
	v_mfma_f32_16x16x32_bf16 v[40:43], v[196:199], v[204:207], v[40:43]
	v_mfma_f32_16x16x32_bf16 v[28:31], v[188:191], v[212:215], v[28:31]
	v_mfma_f32_16x16x32_bf16 v[24:27], v[196:199], v[212:215], v[24:27]
	v_mfma_f32_16x16x32_bf16 v[10:13], v[188:191], v[220:223], v[12:15]
	v_mfma_f32_16x16x32_bf16 v[6:9], v[196:199], v[220:223], v[6:9]
	v_mfma_f32_16x16x32_bf16 v[60:63], v[192:195], v[164:167], v[60:63]
	v_mfma_f32_16x16x32_bf16 v[56:59], v[200:203], v[164:167], v[56:59]
	v_mfma_f32_16x16x32_bf16 v[44:47], v[192:195], v[208:211], v[44:47]
	v_mfma_f32_16x16x32_bf16 v[40:43], v[200:203], v[208:211], v[40:43]
	v_mfma_f32_16x16x32_bf16 v[28:31], v[192:195], v[216:219], v[28:31]
	v_mfma_f32_16x16x32_bf16 v[24:27], v[200:203], v[216:219], v[24:27]
	v_mfma_f32_16x16x32_bf16 v[12:15], v[192:195], v[224:227], v[10:13]
	v_mfma_f32_16x16x32_bf16 v[8:11], v[200:203], v[224:227], v[6:9]
	s_setprio 0
	s_barrier
	s_add_u32 s28, s28, 0x100
	s_addc_u32 s29, s29, 0
	s_add_u32 s73, s73, 0x100
	s_addc_u32 s74, s74, 0
	s_cmp_ge_i32 s12, s67
	s_cbranch_scc0 .LBB0_221
.Lp1b_epi:
	s_and_b64 vcc, exec, s[14:15]
	s_cbranch_vccz .LBB0_239

.LBB0_327:
	s_add_i32 s8, s74, 2
	s_add_u32 s34, s30, 0xfff80080
	s_addc_u32 s35, s31, -1
	s_cmp_eq_u32 s71, s74
	s_cselect_b32 s37, s67, s35
	s_cselect_b32 s36, s68, s34
	s_cselect_b32 s35, s69, s73
	s_cselect_b32 s34, s70, s72
	s_cmpk_lt_i32 s3, 0x56
	s_mov_b32 s79, 0xac00
	s_cselect_b32 s78, s79, 0x4000
	s_mul_i32 s74, s78, s33
	s_add_u32 s74, s38, s74
	s_addc_u32 s75, s39, 0
	global_load_dwordx4 v[152:155], v173, s[74:75] nt
	s_add_u32 s76, s74, s78
	s_addc_u32 s77, s75, 0
	global_load_dwordx4 v[156:159], v173, s[76:77] nt
	s_add_i32 s33, s33, 2
	v_add_u32_e32 v174, -2, v174
	ds_read_b128 v[160:163], v177
	ds_read_b128 v[164:167], v177 offset:1024
	ds_read_b128 v[168:171], v177 offset:2048
	ds_read_b128 v[182:185], v177 offset:3072
	ds_read_b128 v[186:189], v177 offset:16384
	ds_read_b128 v[190:193], v177 offset:17408
	ds_read_b128 v[194:197], v177 offset:18432
	ds_read_b128 v[198:201], v177 offset:19456
	s_add_i32 m0, s46, 0xc000
	ds_read_b128 v[202:205], v180
	ds_read_b128 v[206:209], v180 offset:1024
	ds_read_b128 v[210:213], v180 offset:2048
	ds_read_b128 v[214:217], v180 offset:3072
	ds_read_b128 v[218:221], v180 offset:4096
	ds_read_b128 v[222:225], v180 offset:5120
	ds_read_b128 v[226:229], v180 offset:6144
	global_load_lds_dwordx4 v146, s[30:31]
	s_add_i32 m0, s46, 0xe000
	ds_read_b128 v[230:233], v180 offset:7168
	global_load_lds_dwordx4 v148, s[30:31]
	s_waitcnt vmcnt(10) lgkmcnt(0)
	s_barrier
	s_setprio 1
	v_mfma_i32_16x16x64_i8 v[132:135], v[160:163], v[202:205], v[132:135]
	v_mfma_i32_16x16x64_i8 v[128:131], v[168:171], v[202:205], v[128:131]
	v_mfma_i32_16x16x64_i8 v[124:127], v[160:163], v[210:213], v[124:127]
	v_mfma_i32_16x16x64_i8 v[120:123], v[168:171], v[210:213], v[120:123]
	v_mfma_i32_16x16x64_i8 v[112:115], v[160:163], v[218:221], v[112:115]
	v_mfma_i32_16x16x64_i8 v[104:107], v[168:171], v[218:221], v[104:107]
	v_mfma_i32_16x16x64_i8 v[96:99], v[160:163], v[226:229], v[96:99]
	v_mfma_i32_16x16x64_i8 v[88:91], v[168:171], v[226:229], v[88:91]
	v_mfma_i32_16x16x64_i8 v[132:135], v[164:167], v[206:209], v[132:135]
	v_mfma_i32_16x16x64_i8 v[128:131], v[182:185], v[206:209], v[128:131]
	v_mfma_i32_16x16x64_i8 v[124:127], v[164:167], v[214:217], v[124:127]
	v_mfma_i32_16x16x64_i8 v[120:123], v[182:185], v[214:217], v[120:123]
	v_mfma_i32_16x16x64_i8 v[112:115], v[164:167], v[222:225], v[112:115]
	v_mfma_i32_16x16x64_i8 v[104:107], v[182:185], v[222:225], v[104:107]
	v_mfma_i32_16x16x64_i8 v[96:99], v[164:167], v[230:233], v[96:99]
	v_mfma_i32_16x16x64_i8 v[88:91], v[182:185], v[230:233], v[88:91]
	s_setprio 0
	s_setprio 1
	v_mfma_i32_16x16x64_i8 v[116:119], v[186:189], v[202:205], v[116:119]
	v_mfma_i32_16x16x64_i8 v[108:111], v[194:197], v[202:205], v[108:111]
	v_mfma_i32_16x16x64_i8 v[100:103], v[186:189], v[210:213], v[100:103]
	v_mfma_i32_16x16x64_i8 v[92:95], v[194:197], v[210:213], v[92:95]
	v_mfma_i32_16x16x64_i8 v[84:87], v[186:189], v[218:221], v[84:87]
	v_mfma_i32_16x16x64_i8 v[80:83], v[194:197], v[218:221], v[80:83]
	v_mfma_i32_16x16x64_i8 v[76:79], v[186:189], v[226:229], v[76:79]
	v_mfma_i32_16x16x64_i8 v[72:75], v[194:197], v[226:229], v[72:75]
	v_mfma_i32_16x16x64_i8 v[116:119], v[190:193], v[206:209], v[116:119]
	v_mfma_i32_16x16x64_i8 v[108:111], v[198:201], v[206:209], v[108:111]
	v_mfma_i32_16x16x64_i8 v[100:103], v[190:193], v[214:217], v[100:103]
	v_mfma_i32_16x16x64_i8 v[92:95], v[198:201], v[214:217], v[92:95]
	v_mfma_i32_16x16x64_i8 v[84:87], v[190:193], v[222:225], v[84:87]
	v_mfma_i32_16x16x64_i8 v[80:83], v[198:201], v[222:225], v[80:83]
	v_mfma_i32_16x16x64_i8 v[76:79], v[190:193], v[230:233], v[76:79]
	v_mfma_i32_16x16x64_i8 v[72:75], v[198:201], v[230:233], v[72:75]
	s_setprio 0
	s_barrier
	s_add_i32 s74, s57, s45
	s_mov_b32 m0, s74
	ds_read_b128 v[202:205], v180 offset:16384
	ds_read_b128 v[206:209], v180 offset:17408
	ds_read_b128 v[210:213], v180 offset:18432
	ds_read_b128 v[214:217], v180 offset:19456
	global_load_lds_dwordx4 v138, s[34:35]
	s_add_i32 m0, s74, 0x2000
	s_add_u32 s74, s34, 0x80000
	s_addc_u32 s75, s35, 0
	s_add_i32 s76, s58, s45
	global_load_lds_dwordx4 v142, s[34:35]
	s_mov_b32 m0, s76
	ds_read_b128 v[230:233], v180 offset:23552
	global_load_lds_dwordx4 v138, s[74:75]
	s_add_i32 m0, s76, 0x2000
	ds_read_b128 v[226:229], v180 offset:22528
	global_load_lds_dwordx4 v142, s[74:75]
	s_mov_b32 m0, s46
	ds_read_b128 v[222:225], v180 offset:21504
	global_load_lds_dwordx4 v136, s[36:37]
	s_mov_b32 m0, s47
	ds_read_b128 v[218:221], v180 offset:20480
	global_load_lds_dwordx4 v140, s[36:37]
	s_waitcnt vmcnt(10) lgkmcnt(0)
	s_barrier
	s_setprio 1
	v_mfma_i32_16x16x64_i8 v[68:71], v[160:163], v[202:205], v[68:71]
	v_mfma_i32_16x16x64_i8 v[64:67], v[168:171], v[202:205], v[64:67]
	v_mfma_i32_16x16x64_i8 v[60:63], v[160:163], v[210:213], v[60:63]
	v_mfma_i32_16x16x64_i8 v[56:59], v[168:171], v[210:213], v[56:59]
	v_mfma_i32_16x16x64_i8 v[48:51], v[160:163], v[218:221], v[48:51]
	v_mfma_i32_16x16x64_i8 v[40:43], v[168:171], v[218:221], v[40:43]
	v_mfma_i32_16x16x64_i8 v[32:35], v[160:163], v[226:229], v[32:35]
	v_mfma_i32_16x16x64_i8 v[24:27], v[168:171], v[226:229], v[24:27]
	v_mfma_i32_16x16x64_i8 v[68:71], v[164:167], v[206:209], v[68:71]
	v_mfma_i32_16x16x64_i8 v[64:67], v[182:185], v[206:209], v[64:67]
	v_mfma_i32_16x16x64_i8 v[60:63], v[164:167], v[214:217], v[60:63]
	v_mfma_i32_16x16x64_i8 v[56:59], v[182:185], v[214:217], v[56:59]
	v_mfma_i32_16x16x64_i8 v[48:51], v[164:167], v[222:225], v[48:51]
	v_mfma_i32_16x16x64_i8 v[40:43], v[182:185], v[222:225], v[40:43]
	v_mfma_i32_16x16x64_i8 v[32:35], v[164:167], v[230:233], v[32:35]
	v_mfma_i32_16x16x64_i8 v[24:27], v[182:185], v[230:233], v[24:27]
	s_setprio 0
	s_setprio 1
	v_mfma_i32_16x16x64_i8 v[52:55], v[186:189], v[202:205], v[52:55]
	v_mfma_i32_16x16x64_i8 v[44:47], v[194:197], v[202:205], v[44:47]
	v_mfma_i32_16x16x64_i8 v[36:39], v[186:189], v[210:213], v[36:39]
	v_mfma_i32_16x16x64_i8 v[28:31], v[194:197], v[210:213], v[28:31]
	v_mfma_i32_16x16x64_i8 v[20:23], v[186:189], v[218:221], v[20:23]
	v_mfma_i32_16x16x64_i8 v[16:19], v[194:197], v[218:221], v[16:19]
	v_mfma_i32_16x16x64_i8 v[12:15], v[186:189], v[226:229], v[12:15]
	v_mfma_i32_16x16x64_i8 v[6:9], v[194:197], v[226:229], v[8:11]
	v_mfma_i32_16x16x64_i8 v[52:55], v[190:193], v[206:209], v[52:55]
	v_mfma_i32_16x16x64_i8 v[44:47], v[198:201], v[206:209], v[44:47]
	v_mfma_i32_16x16x64_i8 v[36:39], v[190:193], v[214:217], v[36:39]
	v_mfma_i32_16x16x64_i8 v[28:31], v[198:201], v[214:217], v[28:31]
	v_mfma_i32_16x16x64_i8 v[20:23], v[190:193], v[222:225], v[20:23]
	v_mfma_i32_16x16x64_i8 v[16:19], v[198:201], v[222:225], v[16:19]
	v_mfma_i32_16x16x64_i8 v[12:15], v[190:193], v[230:233], v[12:15]
	v_mfma_i32_16x16x64_i8 v[6:9], v[198:201], v[230:233], v[6:9]
	s_setprio 0
	s_barrier
	s_add_i32 s74, 0, 0x18000
	s_add_i32 s75, 0, 0x1c000
	ds_read_b128 v[160:163], v177 offset:32768
	ds_read_b128 v[164:167], v177 offset:33792
	ds_read_b128 v[168:171], v177 offset:34816
	ds_read_b128 v[182:185], v177 offset:35840
	ds_read_b128 v[186:189], v177 offset:49152
	ds_read_b128 v[190:193], v177 offset:50176
	ds_read_b128 v[194:197], v177 offset:51200
	ds_read_b128 v[198:201], v177 offset:52224
	s_add_u32 s36, s36, 0x80000
	s_addc_u32 s37, s37, 0
	s_mov_b32 m0, s48
	ds_read_b128 v[202:205], v180 offset:32768
	ds_read_b128 v[206:209], v180 offset:33792
	ds_read_b128 v[210:213], v180 offset:34816
	ds_read_b128 v[214:217], v180 offset:35840
	ds_read_b128 v[218:221], v180 offset:36864
	ds_read_b128 v[222:225], v180 offset:37888
	ds_read_b128 v[226:229], v180 offset:38912
	global_load_lds_dwordx4 v136, s[36:37]
	s_mov_b32 m0, s49
	ds_read_b128 v[230:233], v180 offset:39936
	global_load_lds_dwordx4 v140, s[36:37]
	s_waitcnt vmcnt(8) lgkmcnt(0)
	s_barrier
	s_setprio 1
	v_mfma_i32_16x16x64_i8 v[132:135], v[160:163], v[202:205], v[132:135]
	v_mfma_i32_16x16x64_i8 v[128:131], v[168:171], v[202:205], v[128:131]
	v_mfma_i32_16x16x64_i8 v[124:127], v[160:163], v[210:213], v[124:127]
	v_mfma_i32_16x16x64_i8 v[120:123], v[168:171], v[210:213], v[120:123]
	v_mfma_i32_16x16x64_i8 v[112:115], v[160:163], v[218:221], v[112:115]
	v_max3_f32 v0, v0, |v152|, |v156|
	v_mfma_i32_16x16x64_i8 v[104:107], v[168:171], v[218:221], v[104:107]
	v_max3_f32 v1, v1, |v153|, |v157|
	v_mfma_i32_16x16x64_i8 v[96:99], v[160:163], v[226:229], v[96:99]
	v_max3_f32 v2, v2, |v154|, |v158|
	v_mfma_i32_16x16x64_i8 v[88:91], v[168:171], v[226:229], v[88:91]
	v_max3_f32 v3, v3, |v155|, |v159|
	v_mfma_i32_16x16x64_i8 v[132:135], v[164:167], v[206:209], v[132:135]
	v_mfma_i32_16x16x64_i8 v[128:131], v[182:185], v[206:209], v[128:131]
	v_mfma_i32_16x16x64_i8 v[124:127], v[164:167], v[214:217], v[124:127]
	v_mfma_i32_16x16x64_i8 v[120:123], v[182:185], v[214:217], v[120:123]
	v_mfma_i32_16x16x64_i8 v[112:115], v[164:167], v[222:225], v[112:115]
	v_mfma_i32_16x16x64_i8 v[104:107], v[182:185], v[222:225], v[104:107]
	v_mfma_i32_16x16x64_i8 v[96:99], v[164:167], v[230:233], v[96:99]
	v_mfma_i32_16x16x64_i8 v[88:91], v[182:185], v[230:233], v[88:91]
	s_setprio 0
	s_setprio 1
	v_mfma_i32_16x16x64_i8 v[116:119], v[186:189], v[202:205], v[116:119]
	v_mfma_i32_16x16x64_i8 v[108:111], v[194:197], v[202:205], v[108:111]
	v_mfma_i32_16x16x64_i8 v[100:103], v[186:189], v[210:213], v[100:103]
	v_mfma_i32_16x16x64_i8 v[92:95], v[194:197], v[210:213], v[92:95]
	v_mfma_i32_16x16x64_i8 v[84:87], v[186:189], v[218:221], v[84:87]
	v_mfma_i32_16x16x64_i8 v[80:83], v[194:197], v[218:221], v[80:83]
	v_mfma_i32_16x16x64_i8 v[76:79], v[186:189], v[226:229], v[76:79]
	v_mfma_i32_16x16x64_i8 v[72:75], v[194:197], v[226:229], v[72:75]
	v_mfma_i32_16x16x64_i8 v[116:119], v[190:193], v[206:209], v[116:119]
	v_mfma_i32_16x16x64_i8 v[108:111], v[198:201], v[206:209], v[108:111]
	v_mfma_i32_16x16x64_i8 v[100:103], v[190:193], v[214:217], v[100:103]
	v_mfma_i32_16x16x64_i8 v[92:95], v[198:201], v[214:217], v[92:95]
	v_mfma_i32_16x16x64_i8 v[84:87], v[190:193], v[222:225], v[84:87]
	v_mfma_i32_16x16x64_i8 v[80:83], v[198:201], v[222:225], v[80:83]
	v_mfma_i32_16x16x64_i8 v[76:79], v[190:193], v[230:233], v[76:79]
	v_mfma_i32_16x16x64_i8 v[72:75], v[198:201], v[230:233], v[72:75]
	s_setprio 0
	s_barrier
	s_add_u32 s98, s34, s14
	s_addc_u32 s99, s35, s15
	s_add_u32 s100, s36, s14
	s_addc_u32 s101, s37, s15
	s_sub_u32 s100, s100, 0x80000
	s_subb_u32 s101, s101, 0
	s_add_i32 s36, s74, s45
	s_mov_b32 m0, s36
	ds_read_b128 v[152:155], v180 offset:49152
	ds_read_b128 v[156:159], v180 offset:50176
	ds_read_b128 v[202:205], v180 offset:51200
	ds_read_b128 v[206:209], v180 offset:52224
	global_load_lds_dwordx4 v138, s[98:99]
	s_add_i32 m0, s36, 0x2000
	s_add_u32 s34, s34, 0x80080
	s_addc_u32 s35, s35, 0
	s_add_i32 s36, s75, s45
	global_load_lds_dwordx4 v142, s[98:99]
	s_mov_b32 m0, s36
	ds_read_b128 v[222:225], v180 offset:56320
	global_load_lds_dwordx4 v138, s[34:35]
	s_add_i32 m0, s36, 0x2000
	ds_read_b128 v[218:221], v180 offset:55296
	global_load_lds_dwordx4 v142, s[34:35]
	s_mov_b32 m0, s54
	ds_read_b128 v[214:217], v180 offset:54272
	global_load_lds_dwordx4 v136, s[100:101]
	s_mov_b32 m0, s55
	ds_read_b128 v[210:213], v180 offset:53248
	global_load_lds_dwordx4 v140, s[100:101]
	s_waitcnt vmcnt(8) lgkmcnt(0)
	s_barrier
	s_setprio 1
	v_mfma_i32_16x16x64_i8 v[68:71], v[160:163], v[152:155], v[68:71]
	v_mfma_i32_16x16x64_i8 v[64:67], v[168:171], v[152:155], v[64:67]
	v_mfma_i32_16x16x64_i8 v[60:63], v[160:163], v[202:205], v[60:63]
	v_mfma_i32_16x16x64_i8 v[56:59], v[168:171], v[202:205], v[56:59]
	v_mfma_i32_16x16x64_i8 v[48:51], v[160:163], v[210:213], v[48:51]
	v_mfma_i32_16x16x64_i8 v[40:43], v[168:171], v[210:213], v[40:43]
	v_mfma_i32_16x16x64_i8 v[32:35], v[160:163], v[218:221], v[32:35]
	v_mfma_i32_16x16x64_i8 v[24:27], v[168:171], v[218:221], v[24:27]
	v_mfma_i32_16x16x64_i8 v[68:71], v[164:167], v[156:159], v[68:71]
	v_mfma_i32_16x16x64_i8 v[64:67], v[182:185], v[156:159], v[64:67]
	v_mfma_i32_16x16x64_i8 v[60:63], v[164:167], v[206:209], v[60:63]
	v_mfma_i32_16x16x64_i8 v[56:59], v[182:185], v[206:209], v[56:59]
	v_mfma_i32_16x16x64_i8 v[48:51], v[164:167], v[214:217], v[48:51]
	v_mfma_i32_16x16x64_i8 v[40:43], v[182:185], v[214:217], v[40:43]
	v_mfma_i32_16x16x64_i8 v[32:35], v[164:167], v[222:225], v[32:35]
	v_mfma_i32_16x16x64_i8 v[24:27], v[182:185], v[222:225], v[24:27]
	s_setprio 0
	s_setprio 1
	v_mfma_i32_16x16x64_i8 v[52:55], v[186:189], v[152:155], v[52:55]
	v_mfma_i32_16x16x64_i8 v[44:47], v[194:197], v[152:155], v[44:47]
	v_mfma_i32_16x16x64_i8 v[36:39], v[186:189], v[202:205], v[36:39]
	v_mfma_i32_16x16x64_i8 v[28:31], v[194:197], v[202:205], v[28:31]
	v_mfma_i32_16x16x64_i8 v[20:23], v[186:189], v[210:213], v[20:23]
	v_mfma_i32_16x16x64_i8 v[16:19], v[194:197], v[210:213], v[16:19]
	v_mfma_i32_16x16x64_i8 v[10:13], v[186:189], v[218:221], v[12:15]
	v_mfma_i32_16x16x64_i8 v[6:9], v[194:197], v[218:221], v[6:9]
	v_mfma_i32_16x16x64_i8 v[52:55], v[190:193], v[156:159], v[52:55]
	v_mfma_i32_16x16x64_i8 v[44:47], v[198:201], v[156:159], v[44:47]
	v_mfma_i32_16x16x64_i8 v[36:39], v[190:193], v[206:209], v[36:39]
	v_mfma_i32_16x16x64_i8 v[28:31], v[198:201], v[206:209], v[28:31]
	v_mfma_i32_16x16x64_i8 v[20:23], v[190:193], v[214:217], v[20:23]
	v_mfma_i32_16x16x64_i8 v[16:19], v[198:201], v[214:217], v[16:19]
	v_mfma_i32_16x16x64_i8 v[12:15], v[190:193], v[222:225], v[10:13]
	v_mfma_i32_16x16x64_i8 v[8:11], v[198:201], v[222:225], v[6:9]
	s_setprio 0
	s_barrier
	s_add_u32 s30, s30, 0x100
	s_addc_u32 s31, s31, 0
	s_add_u32 s72, s72, 0x100
	s_addc_u32 s73, s73, 0
	s_cmp_ge_i32 s8, s66
	s_cbranch_scc0 .LBB0_312

.LBB0_1033:
	s_add_i32 s8, s71, 2
	s_add_u32 s28, s26, 0xfff00080
	s_addc_u32 s29, s27, -1
	s_cmp_eq_u32 s68, s71
	s_cselect_b32 s31, s64, s29
	s_cselect_b32 s30, s65, s28
	s_cselect_b32 s29, s66, s70
	s_cselect_b32 s28, s67, s69
	s_cmpk_lt_i32 s3, 0x56
	s_mov_b32 s76, 0xac00
	s_cselect_b32 s71, s76, 0x4000
	s_mul_i32 s72, s71, s33
	s_add_u32 s72, s34, s72
	s_addc_u32 s73, s35, 0
	global_load_dwordx4 v[152:155], v159, s[72:73] nt
	s_add_u32 s74, s72, s71
	s_addc_u32 s75, s73, 0
	global_load_dwordx4 v[168:171], v159, s[74:75] nt
	s_add_i32 s33, s33, 2
	v_add_u32_e32 v160, -2, v160
	ds_read_b128 v[172:175], v163
	ds_read_b128 v[176:179], v163 offset:1024
	ds_read_b128 v[180:183], v163 offset:2048
	ds_read_b128 v[184:187], v163 offset:3072
	ds_read_b128 v[188:191], v163 offset:16384
	ds_read_b128 v[192:195], v163 offset:17408
	ds_read_b128 v[196:199], v163 offset:18432
	ds_read_b128 v[200:203], v163 offset:19456
	s_add_i32 m0, s43, 0xc000
	ds_read_b128 v[204:207], v166
	ds_read_b128 v[208:211], v166 offset:1024
	ds_read_b128 v[212:215], v166 offset:2048
	ds_read_b128 v[216:219], v166 offset:3072
	ds_read_b128 v[220:223], v166 offset:4096
	ds_read_b128 v[224:227], v166 offset:5120
	ds_read_b128 v[236:239], v166 offset:6144
	global_load_lds_dwordx4 v146, s[26:27]
	s_add_i32 m0, s43, 0xe000
	ds_read_b128 v[240:243], v166 offset:7168
	global_load_lds_dwordx4 v148, s[26:27]
	s_waitcnt vmcnt(10) lgkmcnt(0)
	s_barrier
	s_setprio 1
	v_mfma_f32_16x16x32_bf16 v[132:135], v[172:175], v[204:207], v[132:135]
	v_mfma_f32_16x16x32_bf16 v[128:131], v[180:183], v[204:207], v[128:131]
	v_mfma_f32_16x16x32_bf16 v[116:119], v[172:175], v[212:215], v[116:119]
	v_mfma_f32_16x16x32_bf16 v[112:115], v[180:183], v[212:215], v[112:115]
	v_mfma_f32_16x16x32_bf16 v[100:103], v[172:175], v[220:223], v[100:103]
	v_mfma_f32_16x16x32_bf16 v[96:99], v[180:183], v[220:223], v[96:99]
	v_mfma_f32_16x16x32_bf16 v[84:87], v[172:175], v[236:239], v[84:87]
	v_mfma_f32_16x16x32_bf16 v[80:83], v[180:183], v[236:239], v[80:83]
	v_mfma_f32_16x16x32_bf16 v[132:135], v[176:179], v[208:211], v[132:135]
	v_mfma_f32_16x16x32_bf16 v[128:131], v[184:187], v[208:211], v[128:131]
	v_mfma_f32_16x16x32_bf16 v[116:119], v[176:179], v[216:219], v[116:119]
	v_mfma_f32_16x16x32_bf16 v[112:115], v[184:187], v[216:219], v[112:115]
	v_mfma_f32_16x16x32_bf16 v[100:103], v[176:179], v[224:227], v[100:103]
	v_mfma_f32_16x16x32_bf16 v[96:99], v[184:187], v[224:227], v[96:99]
	v_mfma_f32_16x16x32_bf16 v[84:87], v[176:179], v[240:243], v[84:87]
	v_mfma_f32_16x16x32_bf16 v[80:83], v[184:187], v[240:243], v[80:83]
	s_setprio 0
	s_setprio 1
	v_mfma_f32_16x16x32_bf16 v[124:127], v[188:191], v[204:207], v[124:127]
	v_mfma_f32_16x16x32_bf16 v[120:123], v[196:199], v[204:207], v[120:123]
	v_mfma_f32_16x16x32_bf16 v[108:111], v[188:191], v[212:215], v[108:111]
	v_mfma_f32_16x16x32_bf16 v[104:107], v[196:199], v[212:215], v[104:107]
	v_mfma_f32_16x16x32_bf16 v[92:95], v[188:191], v[220:223], v[92:95]
	v_mfma_f32_16x16x32_bf16 v[88:91], v[196:199], v[220:223], v[88:91]
	v_mfma_f32_16x16x32_bf16 v[76:79], v[188:191], v[236:239], v[76:79]
	v_mfma_f32_16x16x32_bf16 v[72:75], v[196:199], v[236:239], v[72:75]
	v_mfma_f32_16x16x32_bf16 v[124:127], v[192:195], v[208:211], v[124:127]
	v_mfma_f32_16x16x32_bf16 v[120:123], v[200:203], v[208:211], v[120:123]
	v_mfma_f32_16x16x32_bf16 v[108:111], v[192:195], v[216:219], v[108:111]
	v_mfma_f32_16x16x32_bf16 v[104:107], v[200:203], v[216:219], v[104:107]
	v_mfma_f32_16x16x32_bf16 v[92:95], v[192:195], v[224:227], v[92:95]
	v_mfma_f32_16x16x32_bf16 v[88:91], v[200:203], v[224:227], v[88:91]
	v_mfma_f32_16x16x32_bf16 v[76:79], v[192:195], v[240:243], v[76:79]
	v_mfma_f32_16x16x32_bf16 v[72:75], v[200:203], v[240:243], v[72:75]
	s_setprio 0
	s_barrier
	s_add_i32 s71, s53, s40
	s_mov_b32 m0, s71
	ds_read_b128 v[204:207], v166 offset:16384
	ds_read_b128 v[208:211], v166 offset:17408
	ds_read_b128 v[212:215], v166 offset:18432
	ds_read_b128 v[216:219], v166 offset:19456
	global_load_lds_dwordx4 v138, s[28:29]
	s_add_i32 m0, s71, 0x2000
	s_add_u32 s72, s28, 0x100000
	s_addc_u32 s73, s29, 0
	s_add_i32 s71, s54, s40
	global_load_lds_dwordx4 v142, s[28:29]
	s_mov_b32 m0, s71
	ds_read_b128 v[240:243], v166 offset:23552
	global_load_lds_dwordx4 v138, s[72:73]
	s_add_i32 m0, s71, 0x2000
	ds_read_b128 v[236:239], v166 offset:22528
	global_load_lds_dwordx4 v142, s[72:73]
	s_mov_b32 m0, s43
	ds_read_b128 v[224:227], v166 offset:21504
	global_load_lds_dwordx4 v136, s[30:31]
	s_mov_b32 m0, s44
	ds_read_b128 v[220:223], v166 offset:20480
	global_load_lds_dwordx4 v140, s[30:31]
	s_waitcnt vmcnt(10) lgkmcnt(0)
	s_barrier
	s_setprio 1
	v_mfma_f32_16x16x32_bf16 v[68:71], v[172:175], v[204:207], v[68:71]
	v_mfma_f32_16x16x32_bf16 v[64:67], v[180:183], v[204:207], v[64:67]
	v_mfma_f32_16x16x32_bf16 v[52:55], v[172:175], v[212:215], v[52:55]
	v_mfma_f32_16x16x32_bf16 v[48:51], v[180:183], v[212:215], v[48:51]
	v_mfma_f32_16x16x32_bf16 v[36:39], v[172:175], v[220:223], v[36:39]
	v_mfma_f32_16x16x32_bf16 v[32:35], v[180:183], v[220:223], v[32:35]
	v_mfma_f32_16x16x32_bf16 v[20:23], v[172:175], v[236:239], v[20:23]
	v_mfma_f32_16x16x32_bf16 v[16:19], v[180:183], v[236:239], v[16:19]
	v_mfma_f32_16x16x32_bf16 v[68:71], v[176:179], v[208:211], v[68:71]
	v_mfma_f32_16x16x32_bf16 v[64:67], v[184:187], v[208:211], v[64:67]
	v_mfma_f32_16x16x32_bf16 v[52:55], v[176:179], v[216:219], v[52:55]
	v_mfma_f32_16x16x32_bf16 v[48:51], v[184:187], v[216:219], v[48:51]
	v_mfma_f32_16x16x32_bf16 v[36:39], v[176:179], v[224:227], v[36:39]
	v_mfma_f32_16x16x32_bf16 v[32:35], v[184:187], v[224:227], v[32:35]
	v_mfma_f32_16x16x32_bf16 v[20:23], v[176:179], v[240:243], v[20:23]
	v_mfma_f32_16x16x32_bf16 v[16:19], v[184:187], v[240:243], v[16:19]
	s_setprio 0
	s_setprio 1
	v_mfma_f32_16x16x32_bf16 v[60:63], v[188:191], v[204:207], v[60:63]
	v_mfma_f32_16x16x32_bf16 v[56:59], v[196:199], v[204:207], v[56:59]
	v_mfma_f32_16x16x32_bf16 v[44:47], v[188:191], v[212:215], v[44:47]
	v_mfma_f32_16x16x32_bf16 v[40:43], v[196:199], v[212:215], v[40:43]
	v_mfma_f32_16x16x32_bf16 v[28:31], v[188:191], v[220:223], v[28:31]
	v_mfma_f32_16x16x32_bf16 v[24:27], v[196:199], v[220:223], v[24:27]
	v_mfma_f32_16x16x32_bf16 v[12:15], v[188:191], v[236:239], v[12:15]
	v_mfma_f32_16x16x32_bf16 v[6:9], v[196:199], v[236:239], v[8:11]
	v_mfma_f32_16x16x32_bf16 v[60:63], v[192:195], v[208:211], v[60:63]
	v_mfma_f32_16x16x32_bf16 v[56:59], v[200:203], v[208:211], v[56:59]
	v_mfma_f32_16x16x32_bf16 v[44:47], v[192:195], v[216:219], v[44:47]
	v_mfma_f32_16x16x32_bf16 v[40:43], v[200:203], v[216:219], v[40:43]
	v_mfma_f32_16x16x32_bf16 v[28:31], v[192:195], v[224:227], v[28:31]
	v_mfma_f32_16x16x32_bf16 v[24:27], v[200:203], v[224:227], v[24:27]
	v_mfma_f32_16x16x32_bf16 v[12:15], v[192:195], v[240:243], v[12:15]
	v_mfma_f32_16x16x32_bf16 v[6:9], v[200:203], v[240:243], v[6:9]
	s_setprio 0
	s_barrier
	s_add_i32 s71, 0, 0x18000
	s_add_i32 s72, 0, 0x1c000
	ds_read_b128 v[172:175], v163 offset:32768
	ds_read_b128 v[176:179], v163 offset:33792
	ds_read_b128 v[180:183], v163 offset:34816
	ds_read_b128 v[184:187], v163 offset:35840
	ds_read_b128 v[188:191], v163 offset:49152
	ds_read_b128 v[192:195], v163 offset:50176
	ds_read_b128 v[196:199], v163 offset:51200
	ds_read_b128 v[200:203], v163 offset:52224
	s_add_u32 s30, s30, 0x100000
	s_addc_u32 s31, s31, 0
	s_mov_b32 m0, s45
	ds_read_b128 v[204:207], v166 offset:32768
	ds_read_b128 v[208:211], v166 offset:33792
	ds_read_b128 v[212:215], v166 offset:34816
	ds_read_b128 v[216:219], v166 offset:35840
	ds_read_b128 v[220:223], v166 offset:36864
	ds_read_b128 v[224:227], v166 offset:37888
	ds_read_b128 v[236:239], v166 offset:38912
	global_load_lds_dwordx4 v136, s[30:31]
	s_mov_b32 m0, s46
	ds_read_b128 v[240:243], v166 offset:39936
	global_load_lds_dwordx4 v140, s[30:31]
	s_waitcnt vmcnt(8) lgkmcnt(0)
	s_barrier
	s_setprio 1
	v_mfma_f32_16x16x32_bf16 v[132:135], v[172:175], v[204:207], v[132:135]
	v_mfma_f32_16x16x32_bf16 v[128:131], v[180:183], v[204:207], v[128:131]
	v_mfma_f32_16x16x32_bf16 v[116:119], v[172:175], v[212:215], v[116:119]
	v_mfma_f32_16x16x32_bf16 v[112:115], v[180:183], v[212:215], v[112:115]
	v_mfma_f32_16x16x32_bf16 v[100:103], v[172:175], v[220:223], v[100:103]
	v_max3_f32 v0, v0, |v152|, |v168|
	v_mfma_f32_16x16x32_bf16 v[96:99], v[180:183], v[220:223], v[96:99]
	v_max3_f32 v1, v1, |v153|, |v169|
	v_mfma_f32_16x16x32_bf16 v[84:87], v[172:175], v[236:239], v[84:87]
	v_max3_f32 v2, v2, |v154|, |v170|
	v_mfma_f32_16x16x32_bf16 v[80:83], v[180:183], v[236:239], v[80:83]
	v_max3_f32 v3, v3, |v155|, |v171|
	v_mfma_f32_16x16x32_bf16 v[132:135], v[176:179], v[208:211], v[132:135]
	v_mfma_f32_16x16x32_bf16 v[128:131], v[184:187], v[208:211], v[128:131]
	v_mfma_f32_16x16x32_bf16 v[116:119], v[176:179], v[216:219], v[116:119]
	v_mfma_f32_16x16x32_bf16 v[112:115], v[184:187], v[216:219], v[112:115]
	v_mfma_f32_16x16x32_bf16 v[100:103], v[176:179], v[224:227], v[100:103]
	v_mfma_f32_16x16x32_bf16 v[96:99], v[184:187], v[224:227], v[96:99]
	v_mfma_f32_16x16x32_bf16 v[84:87], v[176:179], v[240:243], v[84:87]
	v_mfma_f32_16x16x32_bf16 v[80:83], v[184:187], v[240:243], v[80:83]
	s_setprio 0
	s_setprio 1
	v_mfma_f32_16x16x32_bf16 v[124:127], v[188:191], v[204:207], v[124:127]
	v_mfma_f32_16x16x32_bf16 v[120:123], v[196:199], v[204:207], v[120:123]
	v_mfma_f32_16x16x32_bf16 v[108:111], v[188:191], v[212:215], v[108:111]
	v_mfma_f32_16x16x32_bf16 v[104:107], v[196:199], v[212:215], v[104:107]
	v_mfma_f32_16x16x32_bf16 v[92:95], v[188:191], v[220:223], v[92:95]
	v_mfma_f32_16x16x32_bf16 v[88:91], v[196:199], v[220:223], v[88:91]
	v_mfma_f32_16x16x32_bf16 v[76:79], v[188:191], v[236:239], v[76:79]
	v_mfma_f32_16x16x32_bf16 v[72:75], v[196:199], v[236:239], v[72:75]
	v_mfma_f32_16x16x32_bf16 v[124:127], v[192:195], v[208:211], v[124:127]
	v_mfma_f32_16x16x32_bf16 v[120:123], v[200:203], v[208:211], v[120:123]
	v_mfma_f32_16x16x32_bf16 v[108:111], v[192:195], v[216:219], v[108:111]
	v_mfma_f32_16x16x32_bf16 v[104:107], v[200:203], v[216:219], v[104:107]
	v_mfma_f32_16x16x32_bf16 v[92:95], v[192:195], v[224:227], v[92:95]
	v_mfma_f32_16x16x32_bf16 v[88:91], v[200:203], v[224:227], v[88:91]
	v_mfma_f32_16x16x32_bf16 v[76:79], v[192:195], v[240:243], v[76:79]
	v_mfma_f32_16x16x32_bf16 v[72:75], v[200:203], v[240:243], v[72:75]
	s_setprio 0
	s_barrier
	s_add_u32 s74, s28, s6
	s_addc_u32 s75, s29, s7
	s_add_u32 s76, s30, s6
	s_addc_u32 s77, s31, s7
	s_sub_u32 s76, s76, 0x100000
	s_subb_u32 s77, s77, 0
	s_add_i32 s30, s71, s40
	s_mov_b32 m0, s30
	ds_read_b128 v[152:155], v166 offset:49152
	ds_read_b128 v[168:171], v166 offset:50176
	ds_read_b128 v[204:207], v166 offset:51200
	ds_read_b128 v[208:211], v166 offset:52224
	global_load_lds_dwordx4 v138, s[74:75]
	s_add_i32 m0, s30, 0x2000
	s_add_u32 s28, s28, 0x100080
	s_addc_u32 s29, s29, 0
	s_add_i32 s30, s72, s40
	global_load_lds_dwordx4 v142, s[74:75]
	s_mov_b32 m0, s30
	ds_read_b128 v[224:227], v166 offset:56320
	global_load_lds_dwordx4 v138, s[28:29]
	s_add_i32 m0, s30, 0x2000
	ds_read_b128 v[220:223], v166 offset:55296
	global_load_lds_dwordx4 v142, s[28:29]
	s_mov_b32 m0, s49
	ds_read_b128 v[216:219], v166 offset:54272
	global_load_lds_dwordx4 v136, s[76:77]
	s_mov_b32 m0, s50
	ds_read_b128 v[212:215], v166 offset:53248
	global_load_lds_dwordx4 v140, s[76:77]
	s_waitcnt vmcnt(8) lgkmcnt(0)
	s_barrier
	s_setprio 1
	v_mfma_f32_16x16x32_bf16 v[68:71], v[172:175], v[152:155], v[68:71]
	v_mfma_f32_16x16x32_bf16 v[64:67], v[180:183], v[152:155], v[64:67]
	v_mfma_f32_16x16x32_bf16 v[52:55], v[172:175], v[204:207], v[52:55]
	v_mfma_f32_16x16x32_bf16 v[48:51], v[180:183], v[204:207], v[48:51]
	v_mfma_f32_16x16x32_bf16 v[36:39], v[172:175], v[212:215], v[36:39]
	v_mfma_f32_16x16x32_bf16 v[32:35], v[180:183], v[212:215], v[32:35]
	v_mfma_f32_16x16x32_bf16 v[20:23], v[172:175], v[220:223], v[20:23]
	v_mfma_f32_16x16x32_bf16 v[16:19], v[180:183], v[220:223], v[16:19]
	v_mfma_f32_16x16x32_bf16 v[68:71], v[176:179], v[168:171], v[68:71]
	v_mfma_f32_16x16x32_bf16 v[64:67], v[184:187], v[168:171], v[64:67]
	v_mfma_f32_16x16x32_bf16 v[52:55], v[176:179], v[208:211], v[52:55]
	v_mfma_f32_16x16x32_bf16 v[48:51], v[184:187], v[208:211], v[48:51]
	v_mfma_f32_16x16x32_bf16 v[36:39], v[176:179], v[216:219], v[36:39]
	v_mfma_f32_16x16x32_bf16 v[32:35], v[184:187], v[216:219], v[32:35]
	v_mfma_f32_16x16x32_bf16 v[20:23], v[176:179], v[224:227], v[20:23]
	v_mfma_f32_16x16x32_bf16 v[16:19], v[184:187], v[224:227], v[16:19]
	s_setprio 0
	s_setprio 1
	v_mfma_f32_16x16x32_bf16 v[60:63], v[188:191], v[152:155], v[60:63]
	v_mfma_f32_16x16x32_bf16 v[56:59], v[196:199], v[152:155], v[56:59]
	v_mfma_f32_16x16x32_bf16 v[44:47], v[188:191], v[204:207], v[44:47]
	v_mfma_f32_16x16x32_bf16 v[40:43], v[196:199], v[204:207], v[40:43]
	v_mfma_f32_16x16x32_bf16 v[28:31], v[188:191], v[212:215], v[28:31]
	v_mfma_f32_16x16x32_bf16 v[24:27], v[196:199], v[212:215], v[24:27]
	v_mfma_f32_16x16x32_bf16 v[10:13], v[188:191], v[220:223], v[12:15]
	v_mfma_f32_16x16x32_bf16 v[6:9], v[196:199], v[220:223], v[6:9]
	v_mfma_f32_16x16x32_bf16 v[60:63], v[192:195], v[168:171], v[60:63]
	v_mfma_f32_16x16x32_bf16 v[56:59], v[200:203], v[168:171], v[56:59]
	v_mfma_f32_16x16x32_bf16 v[44:47], v[192:195], v[208:211], v[44:47]
	v_mfma_f32_16x16x32_bf16 v[40:43], v[200:203], v[208:211], v[40:43]
	v_mfma_f32_16x16x32_bf16 v[28:31], v[192:195], v[216:219], v[28:31]
	v_mfma_f32_16x16x32_bf16 v[24:27], v[200:203], v[216:219], v[24:27]
	v_mfma_f32_16x16x32_bf16 v[12:15], v[192:195], v[224:227], v[10:13]
	v_mfma_f32_16x16x32_bf16 v[8:11], v[200:203], v[224:227], v[6:9]
	s_setprio 0
	s_barrier
	s_add_u32 s26, s26, 0x100
	s_addc_u32 s27, s27, 0
	s_add_u32 s69, s69, 0x100
	s_addc_u32 s70, s70, 0
	s_cmp_ge_i32 s8, s63
	s_cbranch_scc0 .LBB0_1018
